# combined: counted-wait EpiGate + trailing-half restore barrier moved behind the unit header (flag s32) + P8 de-renaming + peel + trim15
# speedup vs baseline: 1.0076x; 1.0033x over previous
;     __device__ __forceinline__ void operator()(const f32x4 (&acc)[2][2][4][2], const Unit& u, int wr, int wc, int fr, int fq) const {
;         const int ch0 = u.pn * 128 + wc * 32 + 8 * fq;
;         f32x4 w0[2], w1[2], w2[2];
; #pragma unroll
;         for (int n = 0; n < 2; ++n) { w0[n] = *(const f32x4*)(cw + ch0 + 4 * n); w1[n] = *(const f32x4*)(cw + ldh + ch0 + 4 * n); w2[n] = *(const f32x4*)(cw + 2 * ldh + ch0 + 4 * n); }
;         const bool f1 = fr >= 1, f2 = fr >= 2;
; #pragma unroll
;         for (int ai = 0; ai < 2; ++ai) {
;             const int blk = u.pm * 4 + ai * 2 + wr;
; #pragma unroll
;             for (int m = 0; m < 4; ++m) {
;                 const size_t row = (size_t)(u.pm * BM + ai * HALF + wr * 64 + m * 16 + fr);
;                 float hg[8];
; #pragma unroll
;                 for (int n = 0; n < 2; ++n)
; #pragma unroll
;                     for (int i = 0; i < 4; ++i) {
;                         const float cur = acc[ai][0][m][n][i], prv = (m > 0) ? acc[ai][0][m > 0 ? m - 1 : 0][n][i] : cur;
;                         const float r1c = dpp_ror1(cur), r1p = dpp_ror1(prv), r2c = dpp_ror2(cur), r2p = dpp_ror2(prv);
;                         const float tm1 = f1 ? r1c : r1p, tm2 = f2 ? r2c : r2p;
;                         const float cv = w0[n][i] * tm2 + w1[n][i] * tm1 + w2[n][i] * cur;
;                         hg[4 * n + i] = cv * sigmoidf_(cv) * acc[ai][1][m][n][i];
;                     }
;                 if (m == 0 && fr < 2) {
;                     const f32x4 a0 = acc[ai][0][0][0], a1 = acc[ai][0][0][1], v0 = acc[ai][1][0][0], v1 = acc[ai][1][0][1];
;                     u32x4 wa, wv; wa.x = cvt_pk_bf16(a0[0], a0[1]); wa.y = cvt_pk_bf16(a0[2], a0[3]); wa.z = cvt_pk_bf16(a1[0], a1[1]); wa.w = cvt_pk_bf16(a1[2], a1[3]);
;                     wv.x = cvt_pk_bf16(v0[0], v0[1]); wv.y = cvt_pk_bf16(v0[2], v0[3]); wv.z = cvt_pk_bf16(v1[0], v1[1]); wv.w = cvt_pk_bf16(v1[2], v1[3]);
;                     *(u32x4*)(side + ((size_t)blk * 6 + 2 + fr) * ldh + ch0) = wa; *(u32x4*)(side + ((size_t)blk * 6 + 4 + fr) * ldh + ch0) = wv;
;                 } else {
;                     u32x4 w; w.x = cvt_pk_bf16(hg[0], hg[1]); w.y = cvt_pk_bf16(hg[2], hg[3]); w.z = cvt_pk_bf16(hg[4], hg[5]); w.w = cvt_pk_bf16(hg[6], hg[7]);
;                     *(u32x4*)(HG + row * ldh + ch0) = w;
;                 }
.LBB0_713:
	v_lshl_or_b32 v70, s15, 7, v221
	v_lshlrev_b32_e32 v71, 2, v70
	global_load_dwordx4 v[192:195], v71, s[58:59]
	global_load_dwordx4 v[232:235], v71, s[56:57]
	global_load_dwordx4 v[224:227], v71, s[52:53]
	global_load_dwordx4 v[196:199], v71, s[58:59] offset:16
	global_load_dwordx4 v[236:239], v71, s[56:57] offset:16
	global_load_dwordx4 v[228:231], v71, s[52:53] offset:16
	s_mov_b32 s65, 0x100000
	v_and_b32_e32 v72, 15, v161
	v_cmp_eq_u32_e64 s[16:17], 15, v72
	v_lshlrev_b32_e32 v188, 1, v70
	v_mov_b32_e32 v189, 0
	v_lshl_add_u32 v73, s14, 8, v161
	v_mad_u64_u32 v[170:171], vcc, v73, s92, v[188:189]
	s_lshl_b32 s14, s14, 2
	s_add_i32 s14, s14, s8
	s_mul_i32 s14, s14, 6
	v_add_u32_e32 v73, s14, v72
	v_lshl_add_u64 v[170:171], s[50:51], 0, v[170:171]
	v_mad_u64_u32 v[190:191], vcc, v73, s92, v[188:189]
	s_mov_b64 s[22:23], exec
	s_mov_b32 s14, 0xbfb8aa3b
	s_mov_b32 s15, 0xbfb8aa3b
	s_mov_b32 s24, 1.0
	s_mov_b32 s25, 1.0
	v_lshl_add_u64 v[190:191], s[48:49], 0, v[190:191]
	v_cvt_pk_bf16_f32 v154, v142, v143
	v_cvt_pk_bf16_f32 v155, v144, v145
	v_cvt_pk_bf16_f32 v156, v130, v131
	v_cvt_pk_bf16_f32 v157, v132, v133
	v_cvt_pk_bf16_f32 v204, v150, v151
	v_cvt_pk_bf16_f32 v205, v152, v153
	v_cvt_pk_bf16_f32 v206, v146, v147
	v_cvt_pk_bf16_f32 v207, v148, v149
	v_add_co_u32_e32 v188, vcc, 0xac00, v190
	v_addc_co_u32_e32 v189, vcc, 0, v191, vcc
	v_add_co_u32_e32 v208, vcc, 0x15800, v190
	v_addc_co_u32_e32 v209, vcc, 0, v191, vcc
	s_waitcnt vmcnt(3)
	v_pk_mul_f32 v[70:71], v[192:193], v[142:143]
	v_pk_mul_f32 v[72:73], v[194:195], v[144:145]
	v_fmac_f32_dpp v70, v142, v232 row_ror:1 row_mask:0xf bank_mask:0xf
	v_fmac_f32_dpp v71, v143, v233 row_ror:1 row_mask:0xf bank_mask:0xf
	v_fmac_f32_dpp v72, v144, v234 row_ror:1 row_mask:0xf bank_mask:0xf
	v_fmac_f32_dpp v73, v145, v235 row_ror:1 row_mask:0xf bank_mask:0xf
	v_fmac_f32_dpp v70, v142, v224 row_ror:2 row_mask:0xf bank_mask:0xf
	v_fmac_f32_dpp v71, v143, v225 row_ror:2 row_mask:0xf bank_mask:0xf
	v_fmac_f32_dpp v72, v144, v226 row_ror:2 row_mask:0xf bank_mask:0xf
	v_fmac_f32_dpp v73, v145, v227 row_ror:2 row_mask:0xf bank_mask:0xf
	v_pk_mul_f32 v[200:201], v[70:71], s[14:15]
	v_pk_mul_f32 v[202:203], v[72:73], s[14:15]
	v_exp_f32_e32 v200, v200
	v_exp_f32_e32 v201, v201
	v_exp_f32_e32 v202, v202
	v_exp_f32_e32 v203, v203
	v_pk_add_f32 v[200:201], v[200:201], s[24:25]
	v_pk_add_f32 v[202:203], v[202:203], s[24:25]
	v_rcp_f32_e32 v200, v200
	v_rcp_f32_e32 v201, v201
	v_rcp_f32_e32 v202, v202
	v_rcp_f32_e32 v203, v203
	v_pk_mul_f32 v[70:71], v[70:71], v[200:201]
	v_pk_mul_f32 v[72:73], v[72:73], v[202:203]
	v_pk_mul_f32 v[150:151], v[150:151], v[70:71]
	v_pk_mul_f32 v[152:153], v[152:153], v[72:73]
	s_waitcnt vmcnt(0)
	v_pk_mul_f32 v[70:71], v[196:197], v[130:131]
	v_pk_mul_f32 v[72:73], v[198:199], v[132:133]
	v_fmac_f32_dpp v70, v130, v236 row_ror:1 row_mask:0xf bank_mask:0xf
	v_fmac_f32_dpp v71, v131, v237 row_ror:1 row_mask:0xf bank_mask:0xf
	v_fmac_f32_dpp v72, v132, v238 row_ror:1 row_mask:0xf bank_mask:0xf
	v_fmac_f32_dpp v73, v133, v239 row_ror:1 row_mask:0xf bank_mask:0xf
	v_fmac_f32_dpp v70, v130, v228 row_ror:2 row_mask:0xf bank_mask:0xf
	v_fmac_f32_dpp v71, v131, v229 row_ror:2 row_mask:0xf bank_mask:0xf
	v_fmac_f32_dpp v72, v132, v230 row_ror:2 row_mask:0xf bank_mask:0xf
	v_fmac_f32_dpp v73, v133, v231 row_ror:2 row_mask:0xf bank_mask:0xf
	v_pk_mul_f32 v[200:201], v[70:71], s[14:15]
	v_pk_mul_f32 v[202:203], v[72:73], s[14:15]
	v_exp_f32_e32 v200, v200
	v_exp_f32_e32 v201, v201
	v_exp_f32_e32 v202, v202
	v_exp_f32_e32 v203, v203
	v_pk_add_f32 v[200:201], v[200:201], s[24:25]
	v_pk_add_f32 v[202:203], v[202:203], s[24:25]
	v_rcp_f32_e32 v200, v200
	v_rcp_f32_e32 v201, v201
	v_rcp_f32_e32 v202, v202
	v_rcp_f32_e32 v203, v203
	v_pk_mul_f32 v[70:71], v[70:71], v[200:201]
	v_pk_mul_f32 v[72:73], v[72:73], v[202:203]
	v_pk_mul_f32 v[146:147], v[146:147], v[70:71]
	v_pk_mul_f32 v[148:149], v[148:149], v[72:73]
	s_andn2_b64 exec, s[22:23], s[40:41]
	global_store_dwordx4 v[188:189], v[154:157], off
	global_store_dwordx4 v[208:209], v[204:207], off
	s_mov_b64 exec, s[22:23]
	v_cvt_pk_bf16_f32 v150, v150, v151
	v_cvt_pk_bf16_f32 v151, v152, v153
	v_cvt_pk_bf16_f32 v152, v146, v147
	v_cvt_pk_bf16_f32 v153, v148, v149
	s_and_b64 exec, s[22:23], s[40:41]
	global_store_dwordx4 v[170:171], v[150:153], off
	s_mov_b64 exec, s[22:23]
	v_cndmask_b32_e64 v200, v138, v142, s[16:17]
	v_cndmask_b32_e64 v201, v139, v143, s[16:17]
	v_cndmask_b32_e64 v202, v140, v144, s[16:17]
	v_cndmask_b32_e64 v203, v141, v145, s[16:17]
	v_cndmask_b32_e64 v204, v138, v142, s[42:43]
	v_cndmask_b32_e64 v205, v139, v143, s[42:43]
	v_cndmask_b32_e64 v206, v140, v144, s[42:43]
	v_cndmask_b32_e64 v207, v141, v145, s[42:43]
	v_pk_mul_f32 v[70:71], v[192:193], v[138:139]
	v_pk_mul_f32 v[72:73], v[194:195], v[140:141]
	v_fmac_f32_dpp v70, v200, v232 row_ror:1 row_mask:0xf bank_mask:0xf
	v_fmac_f32_dpp v71, v201, v233 row_ror:1 row_mask:0xf bank_mask:0xf
	v_fmac_f32_dpp v72, v202, v234 row_ror:1 row_mask:0xf bank_mask:0xf
	v_fmac_f32_dpp v73, v203, v235 row_ror:1 row_mask:0xf bank_mask:0xf
	v_fmac_f32_dpp v70, v204, v224 row_ror:2 row_mask:0xf bank_mask:0xf
	v_fmac_f32_dpp v71, v205, v225 row_ror:2 row_mask:0xf bank_mask:0xf
	v_fmac_f32_dpp v72, v206, v226 row_ror:2 row_mask:0xf bank_mask:0xf
	v_fmac_f32_dpp v73, v207, v227 row_ror:2 row_mask:0xf bank_mask:0xf
	v_pk_mul_f32 v[200:201], v[70:71], s[14:15]
	v_pk_mul_f32 v[202:203], v[72:73], s[14:15]
	v_exp_f32_e32 v200, v200
	v_exp_f32_e32 v201, v201
	v_exp_f32_e32 v202, v202
	v_exp_f32_e32 v203, v203
	v_pk_add_f32 v[200:201], v[200:201], s[24:25]
	v_pk_add_f32 v[202:203], v[202:203], s[24:25]
; __device__ __forceinline__ unsigned cvt_pk_bf16(float lo, float hi) { unsigned r; asm volatile("v_cvt_pk_bf16_f32 %0, %1, %2" : "=v"(r) : "v"(lo), "v"(hi)); return r; }
; __device__ __forceinline__ float sigmoidf_(float x) { return __builtin_amdgcn_rcpf(1.0f + __expf(-x)); }
; __device__ __forceinline__ float dpp_ror1(float x) { return __int_as_float(__builtin_amdgcn_update_dpp(0, __float_as_int(x), 0x121, 0xF, 0xF, true)); }
;     __device__ __forceinline__ void operator()(const f32x4 (&acc)[2][2][4][2], const Unit& u, int wr, int wc, int fr, int fq) const {
;     ...
;             for (int m = 0; m < 4; ++m) {
;                 const size_t row = (size_t)(u.pm * BM + ai * HALF + wr * 64 + m * 16 + fr);
;                 float hg[8];
; #pragma unroll
;                 for (int n = 0; n < 2; ++n)
; #pragma unroll
;                     for (int i = 0; i < 4; ++i) {
;                         const float cur = acc[ai][0][m][n][i], prv = (m > 0) ? acc[ai][0][m > 0 ? m - 1 : 0][n][i] : cur;
;                         const float r1c = dpp_ror1(cur), r1p = dpp_ror1(prv), r2c = dpp_ror2(cur), r2p = dpp_ror2(prv);
;                         const float tm1 = f1 ? r1c : r1p, tm2 = f2 ? r2c : r2p;
;                         const float cv = w0[n][i] * tm2 + w1[n][i] * tm1 + w2[n][i] * cur;
;                         hg[4 * n + i] = cv * sigmoidf_(cv) * acc[ai][1][m][n][i];
;                     }
;                 if (m == 0 && fr < 2) {
;                     const f32x4 a0 = acc[ai][0][0][0], a1 = acc[ai][0][0][1], v0 = acc[ai][1][0][0], v1 = acc[ai][1][0][1];
;                     u32x4 wa, wv; wa.x = cvt_pk_bf16(a0[0], a0[1]); wa.y = cvt_pk_bf16(a0[2], a0[3]); wa.z = cvt_pk_bf16(a1[0], a1[1]); wa.w = cvt_pk_bf16(a1[2], a1[3]);
;                     wv.x = cvt_pk_bf16(v0[0], v0[1]); wv.y = cvt_pk_bf16(v0[2], v0[3]); wv.z = cvt_pk_bf16(v1[0], v1[1]); wv.w = cvt_pk_bf16(v1[2], v1[3]);
;                     *(u32x4*)(side + ((size_t)blk * 6 + 2 + fr) * ldh + ch0) = wa; *(u32x4*)(side + ((size_t)blk * 6 + 4 + fr) * ldh + ch0) = wv;
;                 } else {
;                     u32x4 w; w.x = cvt_pk_bf16(hg[0], hg[1]); w.y = cvt_pk_bf16(hg[2], hg[3]); w.z = cvt_pk_bf16(hg[4], hg[5]); w.w = cvt_pk_bf16(hg[6], hg[7]);
;                     *(u32x4*)(HG + row * ldh + ch0) = w;
;                 }
	v_rcp_f32_e32 v200, v200
	v_rcp_f32_e32 v201, v201
	v_rcp_f32_e32 v202, v202
	v_rcp_f32_e32 v203, v203
	v_pk_mul_f32 v[70:71], v[70:71], v[200:201]
	v_pk_mul_f32 v[72:73], v[72:73], v[202:203]
	v_pk_mul_f32 v[134:135], v[134:135], v[70:71]
	v_pk_mul_f32 v[136:137], v[136:137], v[72:73]
	v_cndmask_b32_e64 v200, v126, v130, s[16:17]
	v_cndmask_b32_e64 v201, v127, v131, s[16:17]
	v_cndmask_b32_e64 v202, v128, v132, s[16:17]
	v_cndmask_b32_e64 v203, v129, v133, s[16:17]
	v_cndmask_b32_e64 v204, v126, v130, s[42:43]
	v_cndmask_b32_e64 v205, v127, v131, s[42:43]
	v_cndmask_b32_e64 v206, v128, v132, s[42:43]
	v_cndmask_b32_e64 v207, v129, v133, s[42:43]
	v_pk_mul_f32 v[70:71], v[196:197], v[126:127]
	v_pk_mul_f32 v[72:73], v[198:199], v[128:129]
	v_fmac_f32_dpp v70, v200, v236 row_ror:1 row_mask:0xf bank_mask:0xf
	v_fmac_f32_dpp v71, v201, v237 row_ror:1 row_mask:0xf bank_mask:0xf
	v_fmac_f32_dpp v72, v202, v238 row_ror:1 row_mask:0xf bank_mask:0xf
	v_fmac_f32_dpp v73, v203, v239 row_ror:1 row_mask:0xf bank_mask:0xf
	v_fmac_f32_dpp v70, v204, v228 row_ror:2 row_mask:0xf bank_mask:0xf
	v_fmac_f32_dpp v71, v205, v229 row_ror:2 row_mask:0xf bank_mask:0xf
	v_fmac_f32_dpp v72, v206, v230 row_ror:2 row_mask:0xf bank_mask:0xf
	v_fmac_f32_dpp v73, v207, v231 row_ror:2 row_mask:0xf bank_mask:0xf
	v_pk_mul_f32 v[200:201], v[70:71], s[14:15]
	v_pk_mul_f32 v[202:203], v[72:73], s[14:15]
	v_exp_f32_e32 v200, v200
	v_exp_f32_e32 v201, v201
	v_exp_f32_e32 v202, v202
	v_exp_f32_e32 v203, v203
	v_pk_add_f32 v[200:201], v[200:201], s[24:25]
	v_pk_add_f32 v[202:203], v[202:203], s[24:25]
	v_rcp_f32_e32 v200, v200
	v_rcp_f32_e32 v201, v201
	v_rcp_f32_e32 v202, v202
	v_rcp_f32_e32 v203, v203
	v_pk_mul_f32 v[70:71], v[70:71], v[200:201]
	v_pk_mul_f32 v[72:73], v[72:73], v[202:203]
	v_pk_mul_f32 v[122:123], v[122:123], v[70:71]
	v_pk_mul_f32 v[124:125], v[124:125], v[72:73]
	v_cvt_pk_bf16_f32 v134, v134, v135
	v_cvt_pk_bf16_f32 v135, v136, v137
	v_cvt_pk_bf16_f32 v136, v122, v123
	v_cvt_pk_bf16_f32 v137, v124, v125
	v_add_co_u32_e32 v170, vcc, 0x56000, v170
	v_addc_co_u32_e32 v171, vcc, 0, v171, vcc
	global_store_dwordx4 v[170:171], v[134:137], off
	v_cndmask_b32_e64 v200, v118, v138, s[16:17]
	v_cndmask_b32_e64 v201, v119, v139, s[16:17]
	v_cndmask_b32_e64 v202, v120, v140, s[16:17]
	v_cndmask_b32_e64 v203, v121, v141, s[16:17]
	v_cndmask_b32_e64 v204, v118, v138, s[42:43]
	v_cndmask_b32_e64 v205, v119, v139, s[42:43]
	v_cndmask_b32_e64 v206, v120, v140, s[42:43]
	v_cndmask_b32_e64 v207, v121, v141, s[42:43]
	v_pk_mul_f32 v[70:71], v[192:193], v[118:119]
	v_pk_mul_f32 v[72:73], v[194:195], v[120:121]
	v_fmac_f32_dpp v70, v200, v232 row_ror:1 row_mask:0xf bank_mask:0xf
	v_fmac_f32_dpp v71, v201, v233 row_ror:1 row_mask:0xf bank_mask:0xf
	v_fmac_f32_dpp v72, v202, v234 row_ror:1 row_mask:0xf bank_mask:0xf
	v_fmac_f32_dpp v73, v203, v235 row_ror:1 row_mask:0xf bank_mask:0xf
	v_fmac_f32_dpp v70, v204, v224 row_ror:2 row_mask:0xf bank_mask:0xf
	v_fmac_f32_dpp v71, v205, v225 row_ror:2 row_mask:0xf bank_mask:0xf
	v_fmac_f32_dpp v72, v206, v226 row_ror:2 row_mask:0xf bank_mask:0xf
	v_fmac_f32_dpp v73, v207, v227 row_ror:2 row_mask:0xf bank_mask:0xf
	v_pk_mul_f32 v[200:201], v[70:71], s[14:15]
	v_pk_mul_f32 v[202:203], v[72:73], s[14:15]
	v_exp_f32_e32 v200, v200
	v_exp_f32_e32 v201, v201
	v_exp_f32_e32 v202, v202
	v_exp_f32_e32 v203, v203
	v_pk_add_f32 v[200:201], v[200:201], s[24:25]
	v_pk_add_f32 v[202:203], v[202:203], s[24:25]
	v_rcp_f32_e32 v200, v200
	v_rcp_f32_e32 v201, v201
	v_rcp_f32_e32 v202, v202
	v_rcp_f32_e32 v203, v203
	v_pk_mul_f32 v[70:71], v[70:71], v[200:201]
	v_pk_mul_f32 v[72:73], v[72:73], v[202:203]
	v_pk_mul_f32 v[114:115], v[114:115], v[70:71]
	v_pk_mul_f32 v[116:117], v[116:117], v[72:73]
	v_cndmask_b32_e64 v200, v110, v126, s[16:17]
	v_cndmask_b32_e64 v201, v111, v127, s[16:17]
	v_cndmask_b32_e64 v202, v112, v128, s[16:17]
	v_cndmask_b32_e64 v203, v113, v129, s[16:17]
	v_cndmask_b32_e64 v204, v110, v126, s[42:43]
	v_cndmask_b32_e64 v205, v111, v127, s[42:43]
	v_cndmask_b32_e64 v206, v112, v128, s[42:43]
	v_cndmask_b32_e64 v207, v113, v129, s[42:43]
	v_pk_mul_f32 v[70:71], v[196:197], v[110:111]
	v_pk_mul_f32 v[72:73], v[198:199], v[112:113]
	v_fmac_f32_dpp v70, v200, v236 row_ror:1 row_mask:0xf bank_mask:0xf
	v_fmac_f32_dpp v71, v201, v237 row_ror:1 row_mask:0xf bank_mask:0xf
	v_fmac_f32_dpp v72, v202, v238 row_ror:1 row_mask:0xf bank_mask:0xf
	v_fmac_f32_dpp v73, v203, v239 row_ror:1 row_mask:0xf bank_mask:0xf
	v_fmac_f32_dpp v70, v204, v228 row_ror:2 row_mask:0xf bank_mask:0xf
	v_fmac_f32_dpp v71, v205, v229 row_ror:2 row_mask:0xf bank_mask:0xf
	v_fmac_f32_dpp v72, v206, v230 row_ror:2 row_mask:0xf bank_mask:0xf
	v_fmac_f32_dpp v73, v207, v231 row_ror:2 row_mask:0xf bank_mask:0xf
	v_pk_mul_f32 v[200:201], v[70:71], s[14:15]
	v_pk_mul_f32 v[202:203], v[72:73], s[14:15]
	v_exp_f32_e32 v200, v200
	v_exp_f32_e32 v201, v201
	v_exp_f32_e32 v202, v202
	v_exp_f32_e32 v203, v203
	v_pk_add_f32 v[200:201], v[200:201], s[24:25]
	v_pk_add_f32 v[202:203], v[202:203], s[24:25]
	v_rcp_f32_e32 v200, v200
	v_rcp_f32_e32 v201, v201
	v_rcp_f32_e32 v202, v202
	v_rcp_f32_e32 v203, v203
	v_pk_mul_f32 v[70:71], v[70:71], v[200:201]
	v_pk_mul_f32 v[72:73], v[72:73], v[202:203]
	v_pk_mul_f32 v[106:107], v[106:107], v[70:71]
	v_pk_mul_f32 v[108:109], v[108:109], v[72:73]
	v_cvt_pk_bf16_f32 v114, v114, v115
	v_cvt_pk_bf16_f32 v115, v116, v117
	v_cvt_pk_bf16_f32 v116, v106, v107
	v_cvt_pk_bf16_f32 v117, v108, v109
	v_add_co_u32_e32 v170, vcc, 0x56000, v170
	v_addc_co_u32_e32 v171, vcc, 0, v171, vcc
	global_store_dwordx4 v[170:171], v[114:117], off
; __device__ __forceinline__ float sigmoidf_(float x) { return __builtin_amdgcn_rcpf(1.0f + __expf(-x)); }
;     __device__ __forceinline__ void operator()(const f32x4 (&acc)[2][2][4][2], const Unit& u, int wr, int wc, int fr, int fq) const {
;     ...
;             for (int m = 0; m < 4; ++m) {
;                 const size_t row = (size_t)(u.pm * BM + ai * HALF + wr * 64 + m * 16 + fr);
;                 float hg[8];
; #pragma unroll
;                 for (int n = 0; n < 2; ++n)
; #pragma unroll
;                     for (int i = 0; i < 4; ++i) {
;                         const float cur = acc[ai][0][m][n][i], prv = (m > 0) ? acc[ai][0][m > 0 ? m - 1 : 0][n][i] : cur;
;                         const float r1c = dpp_ror1(cur), r1p = dpp_ror1(prv), r2c = dpp_ror2(cur), r2p = dpp_ror2(prv);
;                         const float tm1 = f1 ? r1c : r1p, tm2 = f2 ? r2c : r2p;
;                         const float cv = w0[n][i] * tm2 + w1[n][i] * tm1 + w2[n][i] * cur;
;                         hg[4 * n + i] = cv * sigmoidf_(cv) * acc[ai][1][m][n][i];
;                     }
;                 if (m == 0 && fr < 2) {
;                     const f32x4 a0 = acc[ai][0][0][0], a1 = acc[ai][0][0][1], v0 = acc[ai][1][0][0], v1 = acc[ai][1][0][1];
;                     u32x4 wa, wv; wa.x = cvt_pk_bf16(a0[0], a0[1]); wa.y = cvt_pk_bf16(a0[2], a0[3]); wa.z = cvt_pk_bf16(a1[0], a1[1]); wa.w = cvt_pk_bf16(a1[2], a1[3]);
;                     wv.x = cvt_pk_bf16(v0[0], v0[1]); wv.y = cvt_pk_bf16(v0[2], v0[3]); wv.z = cvt_pk_bf16(v1[0], v1[1]); wv.w = cvt_pk_bf16(v1[2], v1[3]);
;                     *(u32x4*)(side + ((size_t)blk * 6 + 2 + fr) * ldh + ch0) = wa; *(u32x4*)(side + ((size_t)blk * 6 + 4 + fr) * ldh + ch0) = wv;
;                 } else {
;                     u32x4 w; w.x = cvt_pk_bf16(hg[0], hg[1]); w.y = cvt_pk_bf16(hg[2], hg[3]); w.z = cvt_pk_bf16(hg[4], hg[5]); w.w = cvt_pk_bf16(hg[6], hg[7]);
;                     *(u32x4*)(HG + row * ldh + ch0) = w;
;                 }
;                 if (m == 3 && fr >= 14) {
;                     const f32x4 a0 = acc[ai][0][3][0], a1 = acc[ai][0][3][1];
;                     u32x4 wa; wa.x = cvt_pk_bf16(a0[0], a0[1]); wa.y = cvt_pk_bf16(a0[2], a0[3]); wa.z = cvt_pk_bf16(a1[0], a1[1]); wa.w = cvt_pk_bf16(a1[2], a1[3]);
;                     *(u32x4*)(side + ((size_t)blk * 6 + (fr - 14)) * ldh + ch0) = wa;
;                 }
	v_cndmask_b32_e64 v200, v98, v118, s[16:17]
	v_cndmask_b32_e64 v201, v99, v119, s[16:17]
	v_cndmask_b32_e64 v202, v100, v120, s[16:17]
	v_cndmask_b32_e64 v203, v101, v121, s[16:17]
	v_cndmask_b32_e64 v204, v98, v118, s[42:43]
	v_cndmask_b32_e64 v205, v99, v119, s[42:43]
	v_cndmask_b32_e64 v206, v100, v120, s[42:43]
	v_cndmask_b32_e64 v207, v101, v121, s[42:43]
	v_pk_mul_f32 v[70:71], v[192:193], v[98:99]
	v_pk_mul_f32 v[72:73], v[194:195], v[100:101]
	v_fmac_f32_dpp v70, v200, v232 row_ror:1 row_mask:0xf bank_mask:0xf
	v_fmac_f32_dpp v71, v201, v233 row_ror:1 row_mask:0xf bank_mask:0xf
	v_fmac_f32_dpp v72, v202, v234 row_ror:1 row_mask:0xf bank_mask:0xf
	v_fmac_f32_dpp v73, v203, v235 row_ror:1 row_mask:0xf bank_mask:0xf
	v_fmac_f32_dpp v70, v204, v224 row_ror:2 row_mask:0xf bank_mask:0xf
	v_fmac_f32_dpp v71, v205, v225 row_ror:2 row_mask:0xf bank_mask:0xf
	v_fmac_f32_dpp v72, v206, v226 row_ror:2 row_mask:0xf bank_mask:0xf
	v_fmac_f32_dpp v73, v207, v227 row_ror:2 row_mask:0xf bank_mask:0xf
	v_pk_mul_f32 v[200:201], v[70:71], s[14:15]
	v_pk_mul_f32 v[202:203], v[72:73], s[14:15]
	v_exp_f32_e32 v200, v200
	v_exp_f32_e32 v201, v201
	v_exp_f32_e32 v202, v202
	v_exp_f32_e32 v203, v203
	v_pk_add_f32 v[200:201], v[200:201], s[24:25]
	v_pk_add_f32 v[202:203], v[202:203], s[24:25]
	v_rcp_f32_e32 v200, v200
	v_rcp_f32_e32 v201, v201
	v_rcp_f32_e32 v202, v202
	v_rcp_f32_e32 v203, v203
	v_pk_mul_f32 v[70:71], v[70:71], v[200:201]
	v_pk_mul_f32 v[72:73], v[72:73], v[202:203]
	v_pk_mul_f32 v[102:103], v[102:103], v[70:71]
	v_pk_mul_f32 v[104:105], v[104:105], v[72:73]
	v_cndmask_b32_e64 v200, v94, v110, s[16:17]
	v_cndmask_b32_e64 v201, v95, v111, s[16:17]
	v_cndmask_b32_e64 v202, v96, v112, s[16:17]
	v_cndmask_b32_e64 v203, v97, v113, s[16:17]
	v_cndmask_b32_e64 v204, v94, v110, s[42:43]
	v_cndmask_b32_e64 v205, v95, v111, s[42:43]
	v_cndmask_b32_e64 v206, v96, v112, s[42:43]
	v_cndmask_b32_e64 v207, v97, v113, s[42:43]
	v_pk_mul_f32 v[70:71], v[196:197], v[94:95]
	v_pk_mul_f32 v[72:73], v[198:199], v[96:97]
	v_fmac_f32_dpp v70, v200, v236 row_ror:1 row_mask:0xf bank_mask:0xf
	v_fmac_f32_dpp v71, v201, v237 row_ror:1 row_mask:0xf bank_mask:0xf
	v_fmac_f32_dpp v72, v202, v238 row_ror:1 row_mask:0xf bank_mask:0xf
	v_fmac_f32_dpp v73, v203, v239 row_ror:1 row_mask:0xf bank_mask:0xf
	v_fmac_f32_dpp v70, v204, v228 row_ror:2 row_mask:0xf bank_mask:0xf
	v_fmac_f32_dpp v71, v205, v229 row_ror:2 row_mask:0xf bank_mask:0xf
	v_fmac_f32_dpp v72, v206, v230 row_ror:2 row_mask:0xf bank_mask:0xf
	v_fmac_f32_dpp v73, v207, v231 row_ror:2 row_mask:0xf bank_mask:0xf
	v_pk_mul_f32 v[200:201], v[70:71], s[14:15]
	v_pk_mul_f32 v[202:203], v[72:73], s[14:15]
	v_exp_f32_e32 v200, v200
	v_exp_f32_e32 v201, v201
	v_exp_f32_e32 v202, v202
	v_exp_f32_e32 v203, v203
	v_pk_add_f32 v[200:201], v[200:201], s[24:25]
	v_pk_add_f32 v[202:203], v[202:203], s[24:25]
	v_rcp_f32_e32 v200, v200
	v_rcp_f32_e32 v201, v201
	v_rcp_f32_e32 v202, v202
	v_rcp_f32_e32 v203, v203
	v_pk_mul_f32 v[70:71], v[70:71], v[200:201]
	v_pk_mul_f32 v[72:73], v[72:73], v[202:203]
	v_pk_mul_f32 v[90:91], v[90:91], v[70:71]
	v_pk_mul_f32 v[92:93], v[92:93], v[72:73]
	v_cvt_pk_bf16_f32 v102, v102, v103
	v_cvt_pk_bf16_f32 v103, v104, v105
	v_cvt_pk_bf16_f32 v104, v90, v91
	v_cvt_pk_bf16_f32 v105, v92, v93
	v_add_co_u32_e32 v170, vcc, 0x56000, v170
	v_addc_co_u32_e32 v171, vcc, 0, v171, vcc
	global_store_dwordx4 v[170:171], v[102:105], off
	v_cvt_pk_bf16_f32 v154, v98, v99
	v_cvt_pk_bf16_f32 v155, v100, v101
	v_cvt_pk_bf16_f32 v156, v94, v95
	v_cvt_pk_bf16_f32 v157, v96, v97
	v_add_co_u32_e32 v188, vcc, 0xfffb4c00, v190
	v_addc_co_u32_e32 v189, vcc, -1, v191, vcc
	s_and_b64 exec, s[22:23], s[42:43]
	global_store_dwordx4 v[188:189], v[154:157], off
	s_mov_b64 exec, s[22:23]
	v_cvt_pk_bf16_f32 v154, v62, v63
	v_cvt_pk_bf16_f32 v155, v64, v65
	v_cvt_pk_bf16_f32 v156, v42, v43
	v_cvt_pk_bf16_f32 v157, v44, v45
	v_cvt_pk_bf16_f32 v204, v82, v83
	v_cvt_pk_bf16_f32 v205, v84, v85
	v_cvt_pk_bf16_f32 v206, v78, v79
	v_cvt_pk_bf16_f32 v207, v80, v81
	v_add_co_u32_e32 v188, vcc, 0x4b400, v190
	v_addc_co_u32_e32 v189, vcc, 0, v191, vcc
	v_add_co_u32_e32 v208, vcc, 0x56000, v190
	v_addc_co_u32_e32 v209, vcc, 0, v191, vcc
	v_pk_mul_f32 v[70:71], v[192:193], v[62:63]
	v_pk_mul_f32 v[72:73], v[194:195], v[64:65]
	v_fmac_f32_dpp v70, v62, v232 row_ror:1 row_mask:0xf bank_mask:0xf
	v_fmac_f32_dpp v71, v63, v233 row_ror:1 row_mask:0xf bank_mask:0xf
	v_fmac_f32_dpp v72, v64, v234 row_ror:1 row_mask:0xf bank_mask:0xf
	v_fmac_f32_dpp v73, v65, v235 row_ror:1 row_mask:0xf bank_mask:0xf
	v_fmac_f32_dpp v70, v62, v224 row_ror:2 row_mask:0xf bank_mask:0xf
	v_fmac_f32_dpp v71, v63, v225 row_ror:2 row_mask:0xf bank_mask:0xf
	v_fmac_f32_dpp v72, v64, v226 row_ror:2 row_mask:0xf bank_mask:0xf
	v_fmac_f32_dpp v73, v65, v227 row_ror:2 row_mask:0xf bank_mask:0xf
	v_pk_mul_f32 v[200:201], v[70:71], s[14:15]
	v_pk_mul_f32 v[202:203], v[72:73], s[14:15]
	v_exp_f32_e32 v200, v200
	v_exp_f32_e32 v201, v201
	v_exp_f32_e32 v202, v202
	v_exp_f32_e32 v203, v203
	v_pk_add_f32 v[200:201], v[200:201], s[24:25]
	v_pk_add_f32 v[202:203], v[202:203], s[24:25]
	v_rcp_f32_e32 v200, v200
	v_rcp_f32_e32 v201, v201
	v_rcp_f32_e32 v202, v202
	v_rcp_f32_e32 v203, v203
	v_pk_mul_f32 v[70:71], v[70:71], v[200:201]
	v_pk_mul_f32 v[72:73], v[72:73], v[202:203]
	v_pk_mul_f32 v[82:83], v[82:83], v[70:71]
	v_pk_mul_f32 v[84:85], v[84:85], v[72:73]
	v_pk_mul_f32 v[70:71], v[196:197], v[42:43]
	v_pk_mul_f32 v[72:73], v[198:199], v[44:45]
	v_fmac_f32_dpp v70, v42, v236 row_ror:1 row_mask:0xf bank_mask:0xf
	v_fmac_f32_dpp v71, v43, v237 row_ror:1 row_mask:0xf bank_mask:0xf
; __device__ __forceinline__ unsigned cvt_pk_bf16(float lo, float hi) { unsigned r; asm volatile("v_cvt_pk_bf16_f32 %0, %1, %2" : "=v"(r) : "v"(lo), "v"(hi)); return r; }
; __device__ __forceinline__ float sigmoidf_(float x) { return __builtin_amdgcn_rcpf(1.0f + __expf(-x)); }
; __device__ __forceinline__ float dpp_ror1(float x) { return __int_as_float(__builtin_amdgcn_update_dpp(0, __float_as_int(x), 0x121, 0xF, 0xF, true)); }
; __device__ __forceinline__ float dpp_ror2(float x) { return __int_as_float(__builtin_amdgcn_update_dpp(0, __float_as_int(x), 0x122, 0xF, 0xF, true)); }
;     __device__ __forceinline__ void operator()(const f32x4 (&acc)[2][2][4][2], const Unit& u, int wr, int wc, int fr, int fq) const {
;     ...
;                     for (int i = 0; i < 4; ++i) {
;                         const float cur = acc[ai][0][m][n][i], prv = (m > 0) ? acc[ai][0][m > 0 ? m - 1 : 0][n][i] : cur;
;                         const float r1c = dpp_ror1(cur), r1p = dpp_ror1(prv), r2c = dpp_ror2(cur), r2p = dpp_ror2(prv);
;                         const float tm1 = f1 ? r1c : r1p, tm2 = f2 ? r2c : r2p;
;                         const float cv = w0[n][i] * tm2 + w1[n][i] * tm1 + w2[n][i] * cur;
;                         hg[4 * n + i] = cv * sigmoidf_(cv) * acc[ai][1][m][n][i];
;                     }
;                 if (m == 0 && fr < 2) {
;                     const f32x4 a0 = acc[ai][0][0][0], a1 = acc[ai][0][0][1], v0 = acc[ai][1][0][0], v1 = acc[ai][1][0][1];
;                     u32x4 wa, wv; wa.x = cvt_pk_bf16(a0[0], a0[1]); wa.y = cvt_pk_bf16(a0[2], a0[3]); wa.z = cvt_pk_bf16(a1[0], a1[1]); wa.w = cvt_pk_bf16(a1[2], a1[3]);
;                     wv.x = cvt_pk_bf16(v0[0], v0[1]); wv.y = cvt_pk_bf16(v0[2], v0[3]); wv.z = cvt_pk_bf16(v1[0], v1[1]); wv.w = cvt_pk_bf16(v1[2], v1[3]);
;                     *(u32x4*)(side + ((size_t)blk * 6 + 2 + fr) * ldh + ch0) = wa; *(u32x4*)(side + ((size_t)blk * 6 + 4 + fr) * ldh + ch0) = wv;
;                 } else {
;                     u32x4 w; w.x = cvt_pk_bf16(hg[0], hg[1]); w.y = cvt_pk_bf16(hg[2], hg[3]); w.z = cvt_pk_bf16(hg[4], hg[5]); w.w = cvt_pk_bf16(hg[6], hg[7]);
;                     *(u32x4*)(HG + row * ldh + ch0) = w;
;                 }
	v_fmac_f32_dpp v72, v44, v238 row_ror:1 row_mask:0xf bank_mask:0xf
	v_fmac_f32_dpp v73, v45, v239 row_ror:1 row_mask:0xf bank_mask:0xf
	v_fmac_f32_dpp v70, v42, v228 row_ror:2 row_mask:0xf bank_mask:0xf
	v_fmac_f32_dpp v71, v43, v229 row_ror:2 row_mask:0xf bank_mask:0xf
	v_fmac_f32_dpp v72, v44, v230 row_ror:2 row_mask:0xf bank_mask:0xf
	v_fmac_f32_dpp v73, v45, v231 row_ror:2 row_mask:0xf bank_mask:0xf
	v_pk_mul_f32 v[200:201], v[70:71], s[14:15]
	v_pk_mul_f32 v[202:203], v[72:73], s[14:15]
	v_exp_f32_e32 v200, v200
	v_exp_f32_e32 v201, v201
	v_exp_f32_e32 v202, v202
	v_exp_f32_e32 v203, v203
	v_pk_add_f32 v[200:201], v[200:201], s[24:25]
	v_pk_add_f32 v[202:203], v[202:203], s[24:25]
	v_rcp_f32_e32 v200, v200
	v_rcp_f32_e32 v201, v201
	v_rcp_f32_e32 v202, v202
	v_rcp_f32_e32 v203, v203
	v_pk_mul_f32 v[70:71], v[70:71], v[200:201]
	v_pk_mul_f32 v[72:73], v[72:73], v[202:203]
	v_pk_mul_f32 v[78:79], v[78:79], v[70:71]
	v_pk_mul_f32 v[80:81], v[80:81], v[72:73]
	s_andn2_b64 exec, s[22:23], s[40:41]
	global_store_dwordx4 v[188:189], v[154:157], off
	global_store_dwordx4 v[208:209], v[204:207], off
	s_mov_b64 exec, s[22:23]
	v_cvt_pk_bf16_f32 v82, v82, v83
	v_cvt_pk_bf16_f32 v83, v84, v85
	v_cvt_pk_bf16_f32 v84, v78, v79
	v_cvt_pk_bf16_f32 v85, v80, v81
	v_add_co_u32_e32 v170, vcc, 0x1ae000, v170
	v_addc_co_u32_e32 v171, vcc, 0, v171, vcc
	s_and_b64 exec, s[22:23], s[40:41]
	global_store_dwordx4 v[170:171], v[82:85], off
	s_mov_b64 exec, s[22:23]
	v_cndmask_b32_e64 v200, v58, v62, s[16:17]
	v_cndmask_b32_e64 v201, v59, v63, s[16:17]
	v_cndmask_b32_e64 v202, v60, v64, s[16:17]
	v_cndmask_b32_e64 v203, v61, v65, s[16:17]
	v_cndmask_b32_e64 v204, v58, v62, s[42:43]
	v_cndmask_b32_e64 v205, v59, v63, s[42:43]
	v_cndmask_b32_e64 v206, v60, v64, s[42:43]
	v_cndmask_b32_e64 v207, v61, v65, s[42:43]
	v_pk_mul_f32 v[70:71], v[192:193], v[58:59]
	v_pk_mul_f32 v[72:73], v[194:195], v[60:61]
	v_fmac_f32_dpp v70, v200, v232 row_ror:1 row_mask:0xf bank_mask:0xf
	v_fmac_f32_dpp v71, v201, v233 row_ror:1 row_mask:0xf bank_mask:0xf
	v_fmac_f32_dpp v72, v202, v234 row_ror:1 row_mask:0xf bank_mask:0xf
	v_fmac_f32_dpp v73, v203, v235 row_ror:1 row_mask:0xf bank_mask:0xf
	v_fmac_f32_dpp v70, v204, v224 row_ror:2 row_mask:0xf bank_mask:0xf
	v_fmac_f32_dpp v71, v205, v225 row_ror:2 row_mask:0xf bank_mask:0xf
	v_fmac_f32_dpp v72, v206, v226 row_ror:2 row_mask:0xf bank_mask:0xf
	v_fmac_f32_dpp v73, v207, v227 row_ror:2 row_mask:0xf bank_mask:0xf
	v_pk_mul_f32 v[200:201], v[70:71], s[14:15]
	v_pk_mul_f32 v[202:203], v[72:73], s[14:15]
	v_exp_f32_e32 v200, v200
	v_exp_f32_e32 v201, v201
	v_exp_f32_e32 v202, v202
	v_exp_f32_e32 v203, v203
	v_pk_add_f32 v[200:201], v[200:201], s[24:25]
	v_pk_add_f32 v[202:203], v[202:203], s[24:25]
	v_rcp_f32_e32 v200, v200
	v_rcp_f32_e32 v201, v201
	v_rcp_f32_e32 v202, v202
	v_rcp_f32_e32 v203, v203
	v_pk_mul_f32 v[70:71], v[70:71], v[200:201]
	v_pk_mul_f32 v[72:73], v[72:73], v[202:203]
	v_pk_mul_f32 v[46:47], v[46:47], v[70:71]
	v_pk_mul_f32 v[48:49], v[48:49], v[72:73]
	v_cndmask_b32_e64 v200, v38, v42, s[16:17]
	v_cndmask_b32_e64 v201, v39, v43, s[16:17]
	v_cndmask_b32_e64 v202, v40, v44, s[16:17]
	v_cndmask_b32_e64 v203, v41, v45, s[16:17]
	v_cndmask_b32_e64 v204, v38, v42, s[42:43]
	v_cndmask_b32_e64 v205, v39, v43, s[42:43]
	v_cndmask_b32_e64 v206, v40, v44, s[42:43]
	v_cndmask_b32_e64 v207, v41, v45, s[42:43]
	v_pk_mul_f32 v[70:71], v[196:197], v[38:39]
	v_pk_mul_f32 v[72:73], v[198:199], v[40:41]
	v_fmac_f32_dpp v70, v200, v236 row_ror:1 row_mask:0xf bank_mask:0xf
	v_fmac_f32_dpp v71, v201, v237 row_ror:1 row_mask:0xf bank_mask:0xf
	v_fmac_f32_dpp v72, v202, v238 row_ror:1 row_mask:0xf bank_mask:0xf
	v_fmac_f32_dpp v73, v203, v239 row_ror:1 row_mask:0xf bank_mask:0xf
	v_fmac_f32_dpp v70, v204, v228 row_ror:2 row_mask:0xf bank_mask:0xf
	v_fmac_f32_dpp v71, v205, v229 row_ror:2 row_mask:0xf bank_mask:0xf
	v_fmac_f32_dpp v72, v206, v230 row_ror:2 row_mask:0xf bank_mask:0xf
	v_fmac_f32_dpp v73, v207, v231 row_ror:2 row_mask:0xf bank_mask:0xf
	v_pk_mul_f32 v[200:201], v[70:71], s[14:15]
	v_pk_mul_f32 v[202:203], v[72:73], s[14:15]
	v_exp_f32_e32 v200, v200
	v_exp_f32_e32 v201, v201
	v_exp_f32_e32 v202, v202
	v_exp_f32_e32 v203, v203
	v_pk_add_f32 v[200:201], v[200:201], s[24:25]
	v_pk_add_f32 v[202:203], v[202:203], s[24:25]
	v_rcp_f32_e32 v200, v200
	v_rcp_f32_e32 v201, v201
	v_rcp_f32_e32 v202, v202
	v_rcp_f32_e32 v203, v203
	v_pk_mul_f32 v[70:71], v[70:71], v[200:201]
	v_pk_mul_f32 v[72:73], v[72:73], v[202:203]
	v_pk_mul_f32 v[34:35], v[34:35], v[70:71]
	v_pk_mul_f32 v[36:37], v[36:37], v[72:73]
	v_cvt_pk_bf16_f32 v46, v46, v47
	v_cvt_pk_bf16_f32 v47, v48, v49
	v_cvt_pk_bf16_f32 v48, v34, v35
	v_cvt_pk_bf16_f32 v49, v36, v37
	v_add_co_u32_e32 v170, vcc, 0x56000, v170
	v_addc_co_u32_e32 v171, vcc, 0, v171, vcc
	global_store_dwordx4 v[170:171], v[46:49], off
	v_cndmask_b32_e64 v200, v30, v58, s[16:17]
	v_cndmask_b32_e64 v201, v31, v59, s[16:17]
	v_cndmask_b32_e64 v202, v32, v60, s[16:17]
	v_cndmask_b32_e64 v203, v33, v61, s[16:17]
	v_cndmask_b32_e64 v204, v30, v58, s[42:43]
	v_cndmask_b32_e64 v205, v31, v59, s[42:43]
	v_cndmask_b32_e64 v206, v32, v60, s[42:43]
	v_cndmask_b32_e64 v207, v33, v61, s[42:43]
	v_pk_mul_f32 v[70:71], v[192:193], v[30:31]
	v_pk_mul_f32 v[72:73], v[194:195], v[32:33]
	v_fmac_f32_dpp v70, v200, v232 row_ror:1 row_mask:0xf bank_mask:0xf
	v_fmac_f32_dpp v71, v201, v233 row_ror:1 row_mask:0xf bank_mask:0xf
	v_fmac_f32_dpp v72, v202, v234 row_ror:1 row_mask:0xf bank_mask:0xf
	v_fmac_f32_dpp v73, v203, v235 row_ror:1 row_mask:0xf bank_mask:0xf
	v_fmac_f32_dpp v70, v204, v224 row_ror:2 row_mask:0xf bank_mask:0xf
;     __device__ __forceinline__ void operator()(const f32x4 (&acc)[2][2][4][2], const Unit& u, int wr, int wc, int fr, int fq) const {
;     ...
;                     for (int i = 0; i < 4; ++i) {
;                         const float cur = acc[ai][0][m][n][i], prv = (m > 0) ? acc[ai][0][m > 0 ? m - 1 : 0][n][i] : cur;
;                         const float r1c = dpp_ror1(cur), r1p = dpp_ror1(prv), r2c = dpp_ror2(cur), r2p = dpp_ror2(prv);
;                         const float tm1 = f1 ? r1c : r1p, tm2 = f2 ? r2c : r2p;
;                         const float cv = w0[n][i] * tm2 + w1[n][i] * tm1 + w2[n][i] * cur;
;                         hg[4 * n + i] = cv * sigmoidf_(cv) * acc[ai][1][m][n][i];
;                     }
;                 if (m == 0 && fr < 2) {
;                     const f32x4 a0 = acc[ai][0][0][0], a1 = acc[ai][0][0][1], v0 = acc[ai][1][0][0], v1 = acc[ai][1][0][1];
;                     u32x4 wa, wv; wa.x = cvt_pk_bf16(a0[0], a0[1]); wa.y = cvt_pk_bf16(a0[2], a0[3]); wa.z = cvt_pk_bf16(a1[0], a1[1]); wa.w = cvt_pk_bf16(a1[2], a1[3]);
;                     wv.x = cvt_pk_bf16(v0[0], v0[1]); wv.y = cvt_pk_bf16(v0[2], v0[3]); wv.z = cvt_pk_bf16(v1[0], v1[1]); wv.w = cvt_pk_bf16(v1[2], v1[3]);
;                     *(u32x4*)(side + ((size_t)blk * 6 + 2 + fr) * ldh + ch0) = wa; *(u32x4*)(side + ((size_t)blk * 6 + 4 + fr) * ldh + ch0) = wv;
;                 } else {
;                     u32x4 w; w.x = cvt_pk_bf16(hg[0], hg[1]); w.y = cvt_pk_bf16(hg[2], hg[3]); w.z = cvt_pk_bf16(hg[4], hg[5]); w.w = cvt_pk_bf16(hg[6], hg[7]);
;                     *(u32x4*)(HG + row * ldh + ch0) = w;
;                 }
;                 if (m == 3 && fr >= 14) {
;                     const f32x4 a0 = acc[ai][0][3][0], a1 = acc[ai][0][3][1];
;                     u32x4 wa; wa.x = cvt_pk_bf16(a0[0], a0[1]); wa.y = cvt_pk_bf16(a0[2], a0[3]); wa.z = cvt_pk_bf16(a1[0], a1[1]); wa.w = cvt_pk_bf16(a1[2], a1[3]);
;                     *(u32x4*)(side + ((size_t)blk * 6 + (fr - 14)) * ldh + ch0) = wa;
;                 }
; template <class Epi, class Sched, bool ALIGN_EPI = false, bool SP2 = false>
; __device__ __forceinline__ void gemm_phase(PG8_LAS unsigned char* lds, const Gemm g, const Sched& S, const Epi& E) {
;     ...
;         if constexpr (ALIGN_EPI) { if (wr == 0) PG8_BAR; }
;         if constexpr (!Epi::AFTER_DRAIN) { E(acc, cur, wr, wc, fr, fq); S.done(cur); }
	v_fmac_f32_dpp v71, v205, v225 row_ror:2 row_mask:0xf bank_mask:0xf
	v_fmac_f32_dpp v72, v206, v226 row_ror:2 row_mask:0xf bank_mask:0xf
	v_fmac_f32_dpp v73, v207, v227 row_ror:2 row_mask:0xf bank_mask:0xf
	v_pk_mul_f32 v[200:201], v[70:71], s[14:15]
	v_pk_mul_f32 v[202:203], v[72:73], s[14:15]
	v_exp_f32_e32 v200, v200
	v_exp_f32_e32 v201, v201
	v_exp_f32_e32 v202, v202
	v_exp_f32_e32 v203, v203
	v_pk_add_f32 v[200:201], v[200:201], s[24:25]
	v_pk_add_f32 v[202:203], v[202:203], s[24:25]
	v_rcp_f32_e32 v200, v200
	v_rcp_f32_e32 v201, v201
	v_rcp_f32_e32 v202, v202
	v_rcp_f32_e32 v203, v203
	v_pk_mul_f32 v[70:71], v[70:71], v[200:201]
	v_pk_mul_f32 v[72:73], v[72:73], v[202:203]
	v_pk_mul_f32 v[26:27], v[26:27], v[70:71]
	v_pk_mul_f32 v[28:29], v[28:29], v[72:73]
	v_cndmask_b32_e64 v200, v22, v38, s[16:17]
	v_cndmask_b32_e64 v201, v23, v39, s[16:17]
	v_cndmask_b32_e64 v202, v24, v40, s[16:17]
	v_cndmask_b32_e64 v203, v25, v41, s[16:17]
	v_cndmask_b32_e64 v204, v22, v38, s[42:43]
	v_cndmask_b32_e64 v205, v23, v39, s[42:43]
	v_cndmask_b32_e64 v206, v24, v40, s[42:43]
	v_cndmask_b32_e64 v207, v25, v41, s[42:43]
	v_pk_mul_f32 v[70:71], v[196:197], v[22:23]
	v_pk_mul_f32 v[72:73], v[198:199], v[24:25]
	v_fmac_f32_dpp v70, v200, v236 row_ror:1 row_mask:0xf bank_mask:0xf
	v_fmac_f32_dpp v71, v201, v237 row_ror:1 row_mask:0xf bank_mask:0xf
	v_fmac_f32_dpp v72, v202, v238 row_ror:1 row_mask:0xf bank_mask:0xf
	v_fmac_f32_dpp v73, v203, v239 row_ror:1 row_mask:0xf bank_mask:0xf
	v_fmac_f32_dpp v70, v204, v228 row_ror:2 row_mask:0xf bank_mask:0xf
	v_fmac_f32_dpp v71, v205, v229 row_ror:2 row_mask:0xf bank_mask:0xf
	v_fmac_f32_dpp v72, v206, v230 row_ror:2 row_mask:0xf bank_mask:0xf
	v_fmac_f32_dpp v73, v207, v231 row_ror:2 row_mask:0xf bank_mask:0xf
	v_pk_mul_f32 v[200:201], v[70:71], s[14:15]
	v_pk_mul_f32 v[202:203], v[72:73], s[14:15]
	v_exp_f32_e32 v200, v200
	v_exp_f32_e32 v201, v201
	v_exp_f32_e32 v202, v202
	v_exp_f32_e32 v203, v203
	v_pk_add_f32 v[200:201], v[200:201], s[24:25]
	v_pk_add_f32 v[202:203], v[202:203], s[24:25]
	v_rcp_f32_e32 v200, v200
	v_rcp_f32_e32 v201, v201
	v_rcp_f32_e32 v202, v202
	v_rcp_f32_e32 v203, v203
	v_pk_mul_f32 v[70:71], v[70:71], v[200:201]
	v_pk_mul_f32 v[72:73], v[72:73], v[202:203]
	v_pk_mul_f32 v[18:19], v[18:19], v[70:71]
	v_pk_mul_f32 v[20:21], v[20:21], v[72:73]
	v_cvt_pk_bf16_f32 v26, v26, v27
	v_cvt_pk_bf16_f32 v27, v28, v29
	v_cvt_pk_bf16_f32 v28, v18, v19
	v_cvt_pk_bf16_f32 v29, v20, v21
	v_add_co_u32_e32 v170, vcc, 0x56000, v170
	v_addc_co_u32_e32 v171, vcc, 0, v171, vcc
	global_store_dwordx4 v[170:171], v[26:29], off
	v_cndmask_b32_e64 v200, v10, v30, s[16:17]
	v_cndmask_b32_e64 v201, v11, v31, s[16:17]
	v_cndmask_b32_e64 v202, v12, v32, s[16:17]
	v_cndmask_b32_e64 v203, v13, v33, s[16:17]
	v_cndmask_b32_e64 v204, v10, v30, s[42:43]
	v_cndmask_b32_e64 v205, v11, v31, s[42:43]
	v_cndmask_b32_e64 v206, v12, v32, s[42:43]
	v_cndmask_b32_e64 v207, v13, v33, s[42:43]
	v_pk_mul_f32 v[70:71], v[192:193], v[10:11]
	v_pk_mul_f32 v[72:73], v[194:195], v[12:13]
	v_fmac_f32_dpp v70, v200, v232 row_ror:1 row_mask:0xf bank_mask:0xf
	v_fmac_f32_dpp v71, v201, v233 row_ror:1 row_mask:0xf bank_mask:0xf
	v_fmac_f32_dpp v72, v202, v234 row_ror:1 row_mask:0xf bank_mask:0xf
	v_fmac_f32_dpp v73, v203, v235 row_ror:1 row_mask:0xf bank_mask:0xf
	v_fmac_f32_dpp v70, v204, v224 row_ror:2 row_mask:0xf bank_mask:0xf
	v_fmac_f32_dpp v71, v205, v225 row_ror:2 row_mask:0xf bank_mask:0xf
	v_fmac_f32_dpp v72, v206, v226 row_ror:2 row_mask:0xf bank_mask:0xf
	v_fmac_f32_dpp v73, v207, v227 row_ror:2 row_mask:0xf bank_mask:0xf
	v_pk_mul_f32 v[200:201], v[70:71], s[14:15]
	v_pk_mul_f32 v[202:203], v[72:73], s[14:15]
	v_exp_f32_e32 v200, v200
	v_exp_f32_e32 v201, v201
	v_exp_f32_e32 v202, v202
	v_exp_f32_e32 v203, v203
	v_pk_add_f32 v[200:201], v[200:201], s[24:25]
	v_pk_add_f32 v[202:203], v[202:203], s[24:25]
	v_rcp_f32_e32 v200, v200
	v_rcp_f32_e32 v201, v201
	v_rcp_f32_e32 v202, v202
	v_rcp_f32_e32 v203, v203
	v_pk_mul_f32 v[70:71], v[70:71], v[200:201]
	v_pk_mul_f32 v[72:73], v[72:73], v[202:203]
	v_pk_mul_f32 v[14:15], v[14:15], v[70:71]
	v_pk_mul_f32 v[16:17], v[16:17], v[72:73]
	v_cndmask_b32_e64 v200, v6, v22, s[16:17]
	v_cndmask_b32_e64 v201, v7, v23, s[16:17]
	v_cndmask_b32_e64 v202, v8, v24, s[16:17]
	v_cndmask_b32_e64 v203, v9, v25, s[16:17]
	v_cndmask_b32_e64 v204, v6, v22, s[42:43]
	v_cndmask_b32_e64 v205, v7, v23, s[42:43]
	v_cndmask_b32_e64 v206, v8, v24, s[42:43]
	v_cndmask_b32_e64 v207, v9, v25, s[42:43]
	v_pk_mul_f32 v[70:71], v[196:197], v[6:7]
	v_pk_mul_f32 v[72:73], v[198:199], v[8:9]
	v_fmac_f32_dpp v70, v200, v236 row_ror:1 row_mask:0xf bank_mask:0xf
	v_fmac_f32_dpp v71, v201, v237 row_ror:1 row_mask:0xf bank_mask:0xf
	v_fmac_f32_dpp v72, v202, v238 row_ror:1 row_mask:0xf bank_mask:0xf
	v_fmac_f32_dpp v73, v203, v239 row_ror:1 row_mask:0xf bank_mask:0xf
	v_fmac_f32_dpp v70, v204, v228 row_ror:2 row_mask:0xf bank_mask:0xf
	v_fmac_f32_dpp v71, v205, v229 row_ror:2 row_mask:0xf bank_mask:0xf
	v_fmac_f32_dpp v72, v206, v230 row_ror:2 row_mask:0xf bank_mask:0xf
	v_fmac_f32_dpp v73, v207, v231 row_ror:2 row_mask:0xf bank_mask:0xf
	v_pk_mul_f32 v[200:201], v[70:71], s[14:15]
	v_pk_mul_f32 v[202:203], v[72:73], s[14:15]
	v_exp_f32_e32 v200, v200
	v_exp_f32_e32 v201, v201
	v_exp_f32_e32 v202, v202
	v_exp_f32_e32 v203, v203
	v_pk_add_f32 v[200:201], v[200:201], s[24:25]
	v_pk_add_f32 v[202:203], v[202:203], s[24:25]
	v_rcp_f32_e32 v200, v200
	v_rcp_f32_e32 v201, v201
	v_rcp_f32_e32 v202, v202
	v_rcp_f32_e32 v203, v203
	v_pk_mul_f32 v[70:71], v[70:71], v[200:201]
	v_pk_mul_f32 v[72:73], v[72:73], v[202:203]
	v_pk_mul_f32 v[2:3], v[2:3], v[70:71]
	v_pk_mul_f32 v[4:5], v[4:5], v[72:73]
	v_cvt_pk_bf16_f32 v14, v14, v15
	v_cvt_pk_bf16_f32 v15, v16, v17
	v_cvt_pk_bf16_f32 v16, v2, v3
	v_cvt_pk_bf16_f32 v17, v4, v5
	v_add_co_u32_e32 v170, vcc, 0x56000, v170
	v_addc_co_u32_e32 v171, vcc, 0, v171, vcc
	global_store_dwordx4 v[170:171], v[14:17], off
	v_cvt_pk_bf16_f32 v154, v10, v11
	v_cvt_pk_bf16_f32 v155, v12, v13
	v_cvt_pk_bf16_f32 v156, v6, v7
	v_cvt_pk_bf16_f32 v157, v8, v9
	v_add_co_u32_e32 v188, vcc, 0xffff5400, v190
	v_addc_co_u32_e32 v189, vcc, -1, v191, vcc
	s_and_b64 exec, s[22:23], s[42:43]
	global_store_dwordx4 v[188:189], v[154:157], off
	s_mov_b64 exec, s[22:23]
	s_andn2_b64 vcc, exec, s[20:21]
	s_mov_b64 s[20:21], -1
	s_cbranch_vccnz .LBB0_699
	s_andn2_b64 vcc, exec, s[46:47]
	s_cbranch_vccnz .LBB0_698
	s_mov_b32 s32, 1
	s_branch .LBB0_698
